# attention unit: K tiles 0-2 / V tiles 0-1 issued by LDS-DMA before the query rows are loaded and normalised (their HBM latency overlaps the unit prologue)
# baseline (speedup 1.0000x reference)
; #define LAS __attribute__((address_space(3)))
; DEV void attn_unit(int b, int h, int qb, const bf16_t* Q, const bf16_t* K, const bf16_t* V, bf16_t* O, LAS unsigned char* sh, const int tid, const float* qgain) {
;     const int lane = tid & 63, r32 = lane & 31, hi = lane >> 5; const int wid = __builtin_amdgcn_readfirstlane(tid >> 6);
;     const long qrow0 = (long)b * SEQ + qb * 256 + wid * 32;
;     const bf16_t* Qw = Q + qrow0 * 1536 + h * 96;
;     const unsigned lds0 = (unsigned)(uintptr_t)sh;
;     LAS float* wsf = (LAS float*)(sh + OFF_WS) + wid * 64;
;     bf16x8 qr[6];
; #pragma unroll
;     for (int d0 = 0; d0 < 6; ++d0) qr[d0] = *(const bf16x8*)(Qw + (long)r32 * 1536 + d0 * 16 + hi * 8);
.LBB0_2104:
	s_lshl_b32 s4, s31, 5
	s_add_i32 s7, s30, s4
	v_readlane_b32 s4, v248, 2
	s_add_i32 s6, s31, s1
	v_readlane_b32 s5, v248, 3
	s_and_b64 s[4:5], s[4:5], exec
	s_cselect_b32 s18, s7, s6
	s_cmpk_gt_i32 s18, 0x7ff
	s_mov_b64 s[4:5], -1
	s_cbranch_scc1 .LBB0_2103
	s_ashr_i32 s4, s18, 8
	v_readfirstlane_b32 s19, v135
	s_ashr_i32 s5, s4, 31
	s_ashr_i32 s21, s19, 6
	s_lshl_b64 s[8:9], s[4:5], 12
	s_lshl_b32 s4, s18, 8
	v_readlane_b32 s6, v251, 31
	s_and_b32 s15, s4, 0xf00
	s_lshl_b32 s14, s21, 5
	s_bfe_u32 s20, s18, 0x40004
	v_readlane_b32 s7, v251, 32
	s_or_b32 s4, s8, s15
	s_ashr_i32 s5, s14, 31
	s_load_dwordx2 s[12:13], s[6:7], 0xf0
	s_add_u32 s6, s4, s14
	s_addc_u32 s7, s9, s5
	s_mul_i32 s4, s7, 0xc00
	s_mul_hi_u32 s5, s6, 0xc00
	s_add_i32 s5, s5, s4
	s_mul_i32 s4, s6, 0xc00
	v_readlane_b32 s10, v251, 54
	v_readlane_b32 s11, v251, 55
	s_add_u32 s4, s10, s4
	s_mul_i32 s10, s20, 0x60
	s_addc_u32 s5, s11, s5
	s_lshl_b32 s10, s10, 1
	s_add_u32 s4, s4, s10
	s_addc_u32 s5, s5, 0
	v_mov_b32_e32 v141, v97
	v_lshl_add_u64 v[0:1], s[4:5], 0, v[140:141]
	v_lshlrev_b32_e32 v96, 1, v134
	v_lshl_add_u64 v[16:17], v[0:1], 0, v[96:97]
	s_lshl_b32 s33, s21, 8
	s_lshl_b32 s22, s21, 10
	s_cmp_lt_u32 s21, 4
	s_cselect_b32 s23, 1, 0
	v_lshl_add_u32 v143, v132, 2, s33
	s_lshl_b32 s27, s20, 7
	s_mul_i32 s24, s8, 0xc00
	s_mul_i32 s42, s20, 0xc0
	s_lshl_b32 s25, s21, 4
	s_add_u32 s42, s42, s25
	s_add_u32 s24, s24, s42
	s_lshr_b32 s25, s8, 4
	s_add_u32 s25, s25, 0x8000
	s_mul_i32 s26, s25, 0xc00
	s_add_u32 s26, s26, s42
	v_readlane_b32 s40, v251, 44
	v_readlane_b32 s41, v251, 45
	v_mul_u32_u24_e32 v128, 0xc00, v130
	v_lshlrev_b32_e32 v145, 11, v136
	s_add_u32 s36, s40, s26
	s_addc_u32 s37, s41, 0
	s_add_u32 s40, s40, s24
	s_addc_u32 s41, s41, 0
	s_and_b32 s42, s21, 3
	s_lshl_b32 s42, s42, 4
	s_add_u32 s24, s8, s42
	s_lshl_b32 s24, s24, 11
	s_lshr_b32 s26, s21, 2
	s_lshl_b32 s26, s26, 6
	s_add_u32 s26, s26, s27
	s_add_u32 s24, s24, s26
	s_add_u32 s25, s25, s42
	s_lshl_b32 s25, s25, 11
	s_add_u32 s25, s25, s26
	v_readlane_b32 s34, v251, 35
	v_readlane_b32 s35, v251, 36
	v_add_u32_e32 v129, 0x80, v128
	v_lshl_add_u32 v145, v138, 1, v145
	s_add_u32 s38, s34, s25
	s_addc_u32 s39, s35, 0
	s_add_u32 s34, s34, s24
	s_addc_u32 s35, s35, 0
	v_add_u32_e32 v126, 0x10000, v194
	v_add_u32_e32 v127, 0x10000, v139
	s_add_i32 m0, s22, 0x0
	s_cmp_eq_u32 s23, 0
	global_load_lds_dwordx4 v128, s[40:41]
	s_cbranch_scc1 .Lat_k2_23
	s_add_i32 m0, s22, 0x2000
	s_nop 0
	global_load_lds_dwordx4 v129, s[40:41]
.Lat_k2_23:
	s_add_u32 s40, s40, 0x30000
	s_addc_u32 s41, s41, 0
	s_add_i32 m0, s22, 0x3000
	s_nop 0
	global_load_lds_dwordx4 v145, s[34:35]
	s_add_u32 s34, s34, 0x20000
	s_addc_u32 s35, s35, 0
	s_add_i32 m0, s22, 0x5000
	s_cmp_eq_u32 s23, 0
	global_load_lds_dwordx4 v128, s[40:41]
	s_cbranch_scc1 .Lat_k2_24
	s_add_i32 m0, s22, 0x7000
	s_nop 0
	global_load_lds_dwordx4 v129, s[40:41]
.Lat_k2_24:
	s_add_u32 s40, s40, 0x30000
	s_addc_u32 s41, s41, 0
	s_add_i32 m0, s22, 0x8000
	s_nop 0
	global_load_lds_dwordx4 v145, s[34:35]
	s_add_u32 s34, s34, 0x20000
	s_addc_u32 s35, s35, 0
	s_add_i32 m0, s22, 0x10000
	s_cmp_eq_u32 s23, 0
	global_load_lds_dwordx4 v128, s[40:41]
	s_cbranch_scc1 .Lat_k2_25
	s_add_i32 m0, s22, 0x12000
	s_nop 0
	global_load_lds_dwordx4 v129, s[40:41]
.Lat_k2_25:
	s_add_u32 s40, s40, 0x30000
	s_addc_u32 s41, s41, 0
	global_load_dwordx4 v[0:3], v[16:17], off
	global_load_dwordx4 v[4:7], v[16:17], off offset:32
	global_load_dwordx4 v[8:11], v[16:17], off offset:64
	global_load_dwordx4 v[12:15], v[16:17], off offset:96
	global_load_dwordx4 v[50:53], v[16:17], off offset:128
	global_load_dwordx4 v[54:57], v[16:17], off offset:160
	v_xor_b32_e32 v40, 32, v183
	s_mov_b32 s11, s88
	s_waitcnt vmcnt(5)
	v_and_b32_e32 v17, 0xffff0000, v0
	v_lshlrev_b32_e32 v16, 16, v0
	v_mul_f32_e32 v18, v17, v17
	v_lshlrev_b32_e32 v19, 16, v1
	v_fmac_f32_e32 v18, v16, v16
	v_and_b32_e32 v21, 0xffff0000, v1
	v_fmac_f32_e32 v18, v19, v19
	v_lshlrev_b32_e32 v20, 16, v2
	v_fmac_f32_e32 v18, v21, v21
	v_and_b32_e32 v22, 0xffff0000, v2
	v_fmac_f32_e32 v18, v20, v20
	v_lshlrev_b32_e32 v23, 16, v3
	v_fmac_f32_e32 v18, v22, v22
	v_and_b32_e32 v26, 0xffff0000, v3
	v_fmac_f32_e32 v18, v23, v23
	v_fmac_f32_e32 v18, v26, v26
	s_waitcnt vmcnt(4)
	v_lshlrev_b32_e32 v24, 16, v4
	v_and_b32_e32 v25, 0xffff0000, v4
	v_fmac_f32_e32 v18, v24, v24
	v_lshlrev_b32_e32 v27, 16, v5
	v_fmac_f32_e32 v18, v25, v25
	v_and_b32_e32 v29, 0xffff0000, v5
	v_fmac_f32_e32 v18, v27, v27
	v_lshlrev_b32_e32 v28, 16, v6
	v_fmac_f32_e32 v18, v29, v29
	v_and_b32_e32 v30, 0xffff0000, v6
	v_fmac_f32_e32 v18, v28, v28
	v_lshlrev_b32_e32 v31, 16, v7
	v_fmac_f32_e32 v18, v30, v30
	v_and_b32_e32 v34, 0xffff0000, v7
	v_fmac_f32_e32 v18, v31, v31
	v_fmac_f32_e32 v18, v34, v34
	s_waitcnt vmcnt(3)
	v_lshlrev_b32_e32 v32, 16, v8
	v_and_b32_e32 v33, 0xffff0000, v8
	v_fmac_f32_e32 v18, v32, v32
	v_lshlrev_b32_e32 v35, 16, v9
	v_fmac_f32_e32 v18, v33, v33
	v_and_b32_e32 v37, 0xffff0000, v9
	v_fmac_f32_e32 v18, v35, v35
	v_lshlrev_b32_e32 v36, 16, v10
	v_fmac_f32_e32 v18, v37, v37
	v_and_b32_e32 v38, 0xffff0000, v10
	v_fmac_f32_e32 v18, v36, v36
	v_lshlrev_b32_e32 v39, 16, v11
	v_fmac_f32_e32 v18, v38, v38
	v_and_b32_e32 v49, 0xffff0000, v11
	v_fmac_f32_e32 v18, v39, v39
	v_fmac_f32_e32 v18, v49, v49
	s_waitcnt vmcnt(2)
	v_lshlrev_b32_e32 v47, 16, v12
	v_and_b32_e32 v45, 0xffff0000, v12
	v_fmac_f32_e32 v18, v47, v47
	v_lshlrev_b32_e32 v43, 16, v13
	v_fmac_f32_e32 v18, v45, v45
	v_and_b32_e32 v41, 0xffff0000, v13
	v_fmac_f32_e32 v18, v43, v43
	v_lshlrev_b32_e32 v48, 16, v14
	v_fmac_f32_e32 v18, v41, v41
	v_and_b32_e32 v46, 0xffff0000, v14
	v_fmac_f32_e32 v18, v48, v48
	v_lshlrev_b32_e32 v44, 16, v15
	v_fmac_f32_e32 v18, v46, v46
	v_and_b32_e32 v42, 0xffff0000, v15
	v_fmac_f32_e32 v18, v44, v44
	v_fmac_f32_e32 v18, v42, v42
	s_waitcnt vmcnt(1)
; DEV void attn_unit(int b, int h, int qb, const bf16_t* Q, const bf16_t* K, const bf16_t* V, bf16_t* O, LAS unsigned char* sh, const int tid, const float* qgain) {
;     ...
;         float qv[6][8]; float ss = 0.f;
; #pragma unroll
;         for (int d0 = 0; d0 < 6; ++d0) { const u32x4 raw = __builtin_bit_cast(u32x4, qr[d0]);
;             qv[d0][0] = __uint_as_float(raw.x << 16); qv[d0][1] = __uint_as_float(raw.x & 0xffff0000u); qv[d0][2] = __uint_as_float(raw.y << 16); qv[d0][3] = __uint_as_float(raw.y & 0xffff0000u);
;             qv[d0][4] = __uint_as_float(raw.z << 16); qv[d0][5] = __uint_as_float(raw.z & 0xffff0000u); qv[d0][6] = __uint_as_float(raw.w << 16); qv[d0][7] = __uint_as_float(raw.w & 0xffff0000u);
; #pragma unroll
;             for (int e = 0; e < 8; ++e) ss += qv[d0][e] * qv[d0][e]; }
;         ss += __shfl_xor(ss, 32);
;         const float rstd = 1.0f / sqrtf(ss * (1.f / 96.f) + EPS);
; #pragma unroll
;         for (int d0 = 0; d0 < 6; ++d0) { const f32x4 g0 = *(const f32x4*)(qgain + d0 * 16 + hi * 8), g1 = *(const f32x4*)(qgain + d0 * 16 + hi * 8 + 4);
; #pragma unroll
;             for (int e = 0; e < 4; ++e) { qv[d0][e] *= rstd * g0[e]; qv[d0][4 + e] *= rstd * g1[e]; } }
	v_lshlrev_b32_e32 v6, 16, v50
	v_and_b32_e32 v4, 0xffff0000, v50
	v_fmac_f32_e32 v18, v6, v6
	v_lshlrev_b32_e32 v2, 16, v51
	v_fmac_f32_e32 v18, v4, v4
	v_and_b32_e32 v0, 0xffff0000, v51
	v_fmac_f32_e32 v18, v2, v2
	v_lshlrev_b32_e32 v7, 16, v52
	v_fmac_f32_e32 v18, v0, v0
	v_and_b32_e32 v5, 0xffff0000, v52
	v_fmac_f32_e32 v18, v7, v7
	v_lshlrev_b32_e32 v3, 16, v53
	v_fmac_f32_e32 v18, v5, v5
	v_and_b32_e32 v1, 0xffff0000, v53
	v_fmac_f32_e32 v18, v3, v3
	v_fmac_f32_e32 v18, v1, v1
	s_waitcnt vmcnt(0)
	v_lshlrev_b32_e32 v14, 16, v54
	v_and_b32_e32 v12, 0xffff0000, v54
	v_fmac_f32_e32 v18, v14, v14
	v_lshlrev_b32_e32 v11, 16, v55
	v_fmac_f32_e32 v18, v12, v12
	v_and_b32_e32 v10, 0xffff0000, v55
	v_fmac_f32_e32 v18, v11, v11
	v_lshlrev_b32_e32 v15, 16, v56
	v_fmac_f32_e32 v18, v10, v10
	v_and_b32_e32 v13, 0xffff0000, v56
	v_fmac_f32_e32 v18, v15, v15
	v_and_b32_e32 v8, 0xffff0000, v57
	v_lshlrev_b32_e32 v9, 16, v57
	v_fmac_f32_e32 v18, v13, v13
	v_pk_mul_f32 v[50:51], v[8:9], v[8:9]
	s_nop 0
	v_add_f32_e32 v18, v51, v18
	v_add_f32_e32 v18, v50, v18
	v_and_b32_e32 v50, 64, v183
	v_add_u32_e32 v50, 64, v50
	v_cmp_lt_i32_e32 vcc, v40, v50
	s_nop 1
	v_cndmask_b32_e32 v40, v183, v40, vcc
	v_lshlrev_b32_e32 v141, 2, v40
	ds_bpermute_b32 v40, v141, v18
	s_waitcnt lgkmcnt(0)
	v_lshlrev_b32_e32 v244, 2, v134
	global_load_dwordx4 v[196:199], v244, s[12:13] offset:16
	global_load_dwordx4 v[200:203], v244, s[12:13]
	global_load_dwordx4 v[204:207], v244, s[12:13] offset:80
	global_load_dwordx4 v[208:211], v244, s[12:13] offset:64
	global_load_dwordx4 v[212:215], v244, s[12:13] offset:144
	global_load_dwordx4 v[216:219], v244, s[12:13] offset:128
	global_load_dwordx4 v[220:223], v244, s[12:13] offset:208
	global_load_dwordx4 v[224:227], v244, s[12:13] offset:192
	global_load_dwordx4 v[228:231], v244, s[12:13] offset:272
	global_load_dwordx4 v[232:235], v244, s[12:13] offset:256
	global_load_dwordx4 v[236:239], v244, s[12:13] offset:336
	global_load_dwordx4 v[240:243], v244, s[12:13] offset:320
	v_add_f32_e32 v18, v18, v40
	v_fmamk_f32 v18, v18, 0x3c2aaaab, v180
	v_cmp_gt_f32_e32 vcc, s78, v18
	v_mul_f32_e32 v40, 0x4f800000, v18
	s_nop 0
	v_cndmask_b32_e32 v18, v18, v40, vcc
	v_sqrt_f32_e32 v40, v18
	s_nop 0
	v_add_u32_e32 v50, -1, v40
	v_fma_f32 v51, -v50, v40, v18
	v_cmp_ge_f32_e64 s[4:5], 0, v51
	v_add_u32_e32 v51, 1, v40
	s_nop 0
	v_cndmask_b32_e64 v50, v40, v50, s[4:5]
	v_fma_f32 v40, -v51, v40, v18
	v_cmp_lt_f32_e64 s[4:5], 0, v40
	s_nop 1
	v_cndmask_b32_e64 v40, v50, v51, s[4:5]
	v_mul_f32_e32 v50, 0x37800000, v40
	v_cndmask_b32_e32 v40, v40, v50, vcc
	v_cmp_class_f32_e32 vcc, v18, v181
	s_nop 1
	v_cndmask_b32_e32 v18, v40, v18, vcc
	v_div_scale_f32 v40, s[4:5], v18, v18, 1.0
	v_rcp_f32_e32 v50, v40
	s_add_i32 s4, s14, s15
	s_ashr_i32 s4, s4, 6
	s_cmp_lt_i32 s21, 4
	v_fma_f32 v51, -v40, v50, 1.0
	v_fmac_f32_e32 v50, v51, v50
	v_div_scale_f32 v51, vcc, 1.0, v18, 1.0
	v_mul_f32_e32 v52, v51, v50
	v_fma_f32 v53, -v40, v52, v51
	v_fmac_f32_e32 v52, v53, v50
	v_fma_f32 v40, -v40, v52, v51
	v_div_fmas_f32 v40, v40, v50, v52
	v_lshlrev_b32_e32 v50, 2, v134
	s_waitcnt vmcnt(0)
	v_mov_b32_e32 v52, v196
	v_mov_b32_e32 v53, v197
	v_mov_b32_e32 v54, v198
	v_mov_b32_e32 v55, v199
	v_mov_b32_e32 v56, v200
	v_mov_b32_e32 v57, v201
	v_mov_b32_e32 v58, v202
	v_mov_b32_e32 v59, v203
	v_div_fixup_f32 v40, v40, v18, 1.0
	s_cselect_b64 s[16:17], -1, 0
	s_waitcnt vmcnt(0)
	v_mul_f32_e32 v18, v56, v40
	v_mul_f32_e32 v18, v18, v16
	v_mul_f32_e32 v16, v52, v40
	v_mul_f32_e32 v16, v16, v20
	v_mul_f32_e32 v20, v57, v40
	v_mul_f32_e32 v20, v20, v17
	v_mul_f32_e32 v17, v53, v40
	v_mul_f32_e32 v17, v17, v22
	v_mul_f32_e32 v22, v58, v40
	v_mul_f32_e32 v22, v22, v19
	v_mul_f32_e32 v19, v54, v40
	v_mul_f32_e32 v19, v19, v23
	v_mul_f32_e32 v23, v59, v40
	v_mul_f32_e32 v23, v23, v21
	v_mul_f32_e32 v21, v55, v40
	v_mov_b32_e32 v52, v204
	v_mov_b32_e32 v53, v205
	v_mov_b32_e32 v54, v206
	v_mov_b32_e32 v55, v207
	v_mov_b32_e32 v56, v208
	v_mov_b32_e32 v57, v209
	v_mov_b32_e32 v58, v210
	v_mov_b32_e32 v59, v211
	v_mul_f32_e32 v21, v21, v26
	s_waitcnt vmcnt(0)
	v_mul_f32_e32 v26, v56, v40
	v_mul_f32_e32 v26, v26, v24
	v_mul_f32_e32 v24, v52, v40
	v_mul_f32_e32 v24, v24, v28
	v_mul_f32_e32 v28, v57, v40
	v_mul_f32_e32 v28, v28, v25
	v_mul_f32_e32 v25, v53, v40
	v_mul_f32_e32 v25, v25, v30
	v_mul_f32_e32 v30, v58, v40
	v_mul_f32_e32 v30, v30, v27
	v_mul_f32_e32 v27, v54, v40
	v_mul_f32_e32 v27, v27, v31
	v_mul_f32_e32 v31, v59, v40
	v_mul_f32_e32 v31, v31, v29
	v_mul_f32_e32 v29, v55, v40
	v_mov_b32_e32 v52, v212
	v_mov_b32_e32 v53, v213
	v_mov_b32_e32 v54, v214
	v_mov_b32_e32 v55, v215
	v_mov_b32_e32 v56, v216
	v_mov_b32_e32 v57, v217
	v_mov_b32_e32 v58, v218
	v_mov_b32_e32 v59, v219
	v_mul_f32_e32 v29, v29, v34
	s_waitcnt vmcnt(0)
	v_mul_f32_e32 v34, v56, v40
	v_mul_f32_e32 v34, v34, v32
	v_mul_f32_e32 v32, v52, v40
	v_mul_f32_e32 v32, v32, v36
	v_mul_f32_e32 v36, v57, v40
	v_mul_f32_e32 v36, v36, v33
	v_mul_f32_e32 v33, v53, v40
	v_mul_f32_e32 v33, v33, v38
	v_mul_f32_e32 v38, v58, v40
	v_mul_f32_e32 v38, v38, v35
	v_mul_f32_e32 v35, v54, v40
	v_mul_f32_e32 v35, v35, v39
	v_mul_f32_e32 v39, v59, v40
	v_mul_f32_e32 v39, v39, v37
	v_mul_f32_e32 v37, v55, v40
	v_mov_b32_e32 v52, v220
	v_mov_b32_e32 v53, v221
	v_mov_b32_e32 v54, v222
	v_mov_b32_e32 v55, v223
	v_mov_b32_e32 v56, v224
	v_mov_b32_e32 v57, v225
	v_mov_b32_e32 v58, v226
	v_mov_b32_e32 v59, v227
	v_mul_f32_e32 v37, v37, v49
	s_waitcnt vmcnt(0)
; DEV void attn_unit(int b, int h, int qb, const bf16_t* Q, const bf16_t* K, const bf16_t* V, bf16_t* O, LAS unsigned char* sh, const int tid, const float* qgain) {
;     ...
;         const int tq = qb * 256 + wid * 32 + r32; const float pr = (float)(tq >> 6), pc = (float)(tq & 63);
; #pragma unroll
;         for (int e = 0; e < 8; ++e) { const float invf = exp2f(-(float)e * (13.287712379549449f / 8.f));
;             const float rr_ = pr * invf * 0.15915494309189535f, rc_ = pc * invf * 0.15915494309189535f;
;             const float sr = __builtin_amdgcn_sinf(rr_), cr = __builtin_amdgcn_cosf(rr_), sc_ = __builtin_amdgcn_sinf(rc_), cc = __builtin_amdgcn_cosf(rc_);
;             const float o4 = qv[4][e], o5 = qv[5][e], p4 = __shfl_xor(o4, 32), p5 = __shfl_xor(o5, 32);
;             qv[4][e] = hi ? (p4 * sr + o4 * cr) : (o4 * cr - p4 * sr);
;             qv[5][e] = hi ? (p5 * sc_ + o5 * cc) : (o5 * cc - p5 * sc_); }
	v_mul_f32_e32 v49, v56, v40
	v_mul_f32_e32 v49, v49, v47
	v_mul_f32_e32 v47, v52, v40
	v_mul_f32_e32 v47, v47, v48
	v_mul_f32_e32 v48, v57, v40
	v_mul_f32_e32 v48, v48, v45
	v_mul_f32_e32 v45, v53, v40
	v_mul_f32_e32 v45, v45, v46
	v_mul_f32_e32 v46, v58, v40
	v_mul_f32_e32 v46, v46, v43
	v_mul_f32_e32 v43, v54, v40
	v_mul_f32_e32 v43, v43, v44
	v_mul_f32_e32 v44, v59, v40
	v_mov_b32_e32 v58, v228
	v_mov_b32_e32 v59, v229
	v_mov_b32_e32 v60, v230
	v_mov_b32_e32 v61, v231
	v_mov_b32_e32 v62, v232
	v_mov_b32_e32 v63, v233
	v_mov_b32_e32 v64, v234
	v_mov_b32_e32 v65, v235
	v_mul_f32_e32 v44, v44, v41
	v_mul_f32_e32 v41, v55, v40
	v_mul_f32_e32 v41, v41, v42
	s_waitcnt vmcnt(0)
	v_mul_f32_e32 v42, v62, v40
	v_mul_f32_e32 v57, v42, v6
	v_mul_f32_e32 v6, v58, v40
	v_mul_f32_e32 v53, v6, v7
	v_mul_f32_e32 v6, v63, v40
	v_mul_f32_e32 v56, v6, v4
	v_mul_f32_e32 v4, v59, v40
	v_mul_f32_e32 v52, v4, v5
	v_mul_f32_e32 v4, v64, v40
	v_mul_f32_e32 v55, v4, v2
	v_mul_f32_e32 v2, v60, v40
	v_mul_f32_e32 v51, v2, v3
	v_mul_f32_e32 v2, v65, v40
	v_mul_f32_e32 v54, v2, v0
	v_mul_f32_e32 v0, v61, v40
	v_mul_f32_e32 v42, v0, v1
	v_mov_b32_e32 v0, v236
	v_mov_b32_e32 v1, v237
	v_mov_b32_e32 v2, v238
	v_mov_b32_e32 v3, v239
	v_mov_b32_e32 v4, v240
	v_mov_b32_e32 v5, v241
	v_mov_b32_e32 v6, v242
	v_mov_b32_e32 v7, v243
	s_waitcnt vmcnt(1)
	v_mul_f32_e32 v3, v3, v40
	v_mul_f32_e32 v3, v3, v8
	v_cvt_f32_i32_e32 v8, s4
	s_waitcnt vmcnt(0)
	v_mul_f32_e32 v4, v4, v40
	v_mul_f32_e32 v2, v2, v40
	v_mul_f32_e32 v7, v7, v40
	v_mul_f32_e32 v4, v4, v14
	v_mul_f32_e32 v5, v5, v40
	v_mul_f32_e32 v2, v2, v9
	v_mul_f32_e32 v7, v7, v10
	v_and_or_b32 v9, s14, 32, v132
	v_mul_f32_e32 v10, 0.15915494, v8
	ds_bpermute_b32 v14, v141, v57
	v_mul_f32_e32 v0, v0, v40
	v_mul_f32_e32 v5, v5, v12
	v_mul_f32_e32 v6, v6, v40
	v_cvt_f32_ubyte0_e32 v9, v9
	v_sin_f32_e32 v12, v10
	v_mul_f32_e32 v0, v0, v15
	v_mul_f32_e32 v1, v1, v40
	v_mul_f32_e32 v6, v6, v11
	v_mul_f32_e32 v11, 0.15915494, v9
	ds_bpermute_b32 v15, v141, v4
	v_mul_f32_e32 v1, v1, v13
	v_cos_f32_e32 v10, v10
	v_sin_f32_e32 v13, v11
	v_cos_f32_e32 v11, v11
	s_waitcnt lgkmcnt(1)
	v_mul_f32_e32 v12, v12, v14
	v_cndmask_b32_e64 v12, v12, -v12, s[2:3]
	v_fmac_f32_e32 v12, v10, v57
	s_waitcnt lgkmcnt(0)
	v_mul_f32_e32 v10, v13, v15
	v_cndmask_b32_e64 v10, v10, -v10, s[2:3]
	v_fmac_f32_e32 v10, v11, v4
	v_mul_f32_e32 v4, 0x3ea1e89b, v8
	v_mul_f32_e32 v4, 0.15915494, v4
	ds_bpermute_b32 v15, v141, v56
	v_mul_f32_e32 v11, 0x3ea1e89b, v9
	v_sin_f32_e32 v13, v4
	v_mul_f32_e32 v11, 0.15915494, v11
	ds_bpermute_b32 v40, v141, v5
	v_cos_f32_e32 v4, v4
	v_sin_f32_e32 v14, v11
	v_cos_f32_e32 v11, v11
	s_waitcnt lgkmcnt(1)
	v_mul_f32_e32 v13, v13, v15
	v_cndmask_b32_e64 v13, v13, -v13, s[2:3]
	v_fmac_f32_e32 v13, v4, v56
	s_waitcnt lgkmcnt(0)
	v_mul_f32_e32 v4, v14, v40
	v_cndmask_b32_e64 v4, v4, -v4, s[2:3]
	v_fmac_f32_e32 v4, v11, v5
	v_mul_f32_e32 v5, 0x3dcccccd, v8
	v_mul_f32_e32 v5, 0.15915494, v5
	ds_bpermute_b32 v40, v141, v55
	v_mul_f32_e32 v11, 0x3dcccccd, v9
	v_sin_f32_e32 v14, v5
	v_mul_f32_e32 v11, 0.15915494, v11
	ds_bpermute_b32 v50, v141, v6
	v_cos_f32_e32 v5, v5
	v_sin_f32_e32 v15, v11
	v_cos_f32_e32 v11, v11
	s_waitcnt lgkmcnt(1)
	v_mul_f32_e32 v14, v14, v40
	v_cndmask_b32_e64 v14, v14, -v14, s[2:3]
	v_fmac_f32_e32 v14, v5, v55
	s_waitcnt lgkmcnt(0)
	v_mul_f32_e32 v5, v15, v50
	v_cndmask_b32_e64 v5, v5, -v5, s[2:3]
	v_fmac_f32_e32 v5, v11, v6
	v_mul_f32_e32 v6, 0x3d0186e3, v8
	v_mul_f32_e32 v6, 0.15915494, v6
	ds_bpermute_b32 v50, v141, v54
	v_mul_f32_e32 v11, 0x3d0186e3, v9
	v_sin_f32_e32 v15, v6
	v_mul_f32_e32 v11, 0.15915494, v11
	ds_bpermute_b32 v55, v141, v7
	v_cos_f32_e32 v6, v6
	v_sin_f32_e32 v40, v11
	v_cos_f32_e32 v11, v11
	s_waitcnt lgkmcnt(1)
	v_mul_f32_e32 v15, v15, v50
	v_cndmask_b32_e64 v15, v15, -v15, s[2:3]
	v_fmac_f32_e32 v15, v6, v54
	s_waitcnt lgkmcnt(0)
	v_mul_f32_e32 v6, v40, v55
	v_cndmask_b32_e64 v6, v6, -v6, s[2:3]
	v_fmac_f32_e32 v6, v11, v7
	v_mul_f32_e32 v7, 0x3c23d70b, v8
	v_mul_f32_e32 v7, 0.15915494, v7
	ds_bpermute_b32 v54, v141, v53
	v_mul_f32_e32 v11, 0x3c23d70b, v9
	v_sin_f32_e32 v40, v7
	v_mul_f32_e32 v11, 0.15915494, v11
	ds_bpermute_b32 v55, v141, v0
	v_cos_f32_e32 v7, v7
	v_sin_f32_e32 v50, v11
	v_cos_f32_e32 v11, v11
	s_waitcnt lgkmcnt(1)
	v_mul_f32_e32 v40, v40, v54
	v_cndmask_b32_e64 v40, v40, -v40, s[2:3]
	v_fmac_f32_e32 v40, v7, v53
	s_waitcnt lgkmcnt(0)
	v_mul_f32_e32 v7, v50, v55
	v_cndmask_b32_e64 v7, v7, -v7, s[2:3]
	v_fmac_f32_e32 v7, v11, v0
	v_mul_f32_e32 v0, 0x3b4f3e39, v8
	v_mul_f32_e32 v0, 0.15915494, v0
	ds_bpermute_b32 v54, v141, v52
	v_mul_f32_e32 v11, 0x3b4f3e39, v9
	v_sin_f32_e32 v50, v0
	v_mul_f32_e32 v11, 0.15915494, v11
	ds_bpermute_b32 v55, v141, v1
	v_cos_f32_e32 v0, v0
	v_sin_f32_e32 v53, v11
	v_cos_f32_e32 v11, v11
	s_waitcnt lgkmcnt(1)
	v_mul_f32_e32 v50, v50, v54
	v_cndmask_b32_e64 v50, v50, -v50, s[2:3]
	v_fmac_f32_e32 v50, v0, v52
	s_waitcnt lgkmcnt(0)
	v_mul_f32_e32 v0, v53, v55
	v_cndmask_b32_e64 v0, v0, -v0, s[2:3]
	v_fmac_f32_e32 v0, v11, v1
	v_mul_f32_e32 v1, 0x3a831270, v8
	v_mul_f32_e32 v1, 0.15915494, v1
	ds_bpermute_b32 v54, v141, v51
	v_mul_f32_e32 v11, 0x3a831270, v9
	v_sin_f32_e32 v52, v1
	v_mul_f32_e32 v11, 0.15915494, v11
	ds_bpermute_b32 v55, v141, v2
	v_cos_f32_e32 v1, v1
	v_sin_f32_e32 v53, v11
	v_cos_f32_e32 v11, v11
	s_waitcnt lgkmcnt(1)
	v_mul_f32_e32 v52, v52, v54
	v_cndmask_b32_e64 v52, v52, -v52, s[2:3]
	v_fmac_f32_e32 v52, v1, v51
	s_waitcnt lgkmcnt(0)
; DEV unsigned cvt_pk_bf16(float lo, float hi) { unsigned r; asm volatile("v_cvt_pk_bf16_f32 %0, %1, %2" : "=v"(r) : "v"(lo), "v"(hi)); return r; }
; DEV void attn_unit(int b, int h, int qb, const bf16_t* Q, const bf16_t* K, const bf16_t* V, bf16_t* O, LAS unsigned char* sh, const int tid, const float* qgain) {
;     ...
;         for (int d0 = 0; d0 < 6; ++d0) { u32x4 w; w.x = cvt_pk_bf16(qv[d0][0] * QSCALE, qv[d0][1] * QSCALE); w.y = cvt_pk_bf16(qv[d0][2] * QSCALE, qv[d0][3] * QSCALE);
;             w.z = cvt_pk_bf16(qv[d0][4] * QSCALE, qv[d0][5] * QSCALE); w.w = cvt_pk_bf16(qv[d0][6] * QSCALE, qv[d0][7] * QSCALE); qr[d0] = __builtin_bit_cast(bf16x8, w); }
;     ...
;     float mrun = 0.f, lsum = 0.f; f32x16 o[2]; o[0] = f32x16{}; o[1] = f32x16{}; const f32x16 zero16 = f32x16{};
	v_mul_f32_e32 v1, v53, v55
	v_cndmask_b32_e64 v1, v1, -v1, s[2:3]
	v_fmac_f32_e32 v1, v11, v2
	v_mul_f32_e32 v2, 0x39a5cb61, v8
	v_mul_f32_e32 v2, 0.15915494, v2
	ds_bpermute_b32 v51, v141, v42
	v_mul_f32_e32 v8, 0x39a5cb61, v9
	v_sin_f32_e32 v9, v2
	v_mul_f32_e32 v8, 0.15915494, v8
	ds_bpermute_b32 v53, v141, v3
	v_cos_f32_e32 v2, v2
	v_sin_f32_e32 v11, v8
	v_cos_f32_e32 v8, v8
	s_waitcnt lgkmcnt(1)
	v_mul_f32_e32 v9, v9, v51
	v_cndmask_b32_e64 v9, v9, -v9, s[2:3]
	v_fmac_f32_e32 v9, v2, v42
	s_waitcnt lgkmcnt(0)
	v_mul_f32_e32 v2, v11, v53
	v_cndmask_b32_e64 v2, v2, -v2, s[2:3]
	v_fmac_f32_e32 v2, v8, v3
	v_mul_f32_e32 v3, 0x3e16c740, v18
	v_mul_f32_e32 v8, 0x3e16c740, v20
	v_cvt_pk_bf16_f32 v110, v3, v8
	v_mul_f32_e32 v3, 0x3e16c740, v22
	v_mul_f32_e32 v8, 0x3e16c740, v23
	v_cvt_pk_bf16_f32 v111, v3, v8
	v_mul_f32_e32 v3, 0x3e16c740, v16
	v_mul_f32_e32 v8, 0x3e16c740, v17
	v_cvt_pk_bf16_f32 v112, v3, v8
	v_mul_f32_e32 v3, 0x3e16c740, v19
	v_mul_f32_e32 v8, 0x3e16c740, v21
	v_cvt_pk_bf16_f32 v113, v3, v8
	v_mul_f32_e32 v3, 0x3e16c740, v26
	v_mul_f32_e32 v8, 0x3e16c740, v28
	v_cvt_pk_bf16_f32 v106, v3, v8
	v_mul_f32_e32 v3, 0x3e16c740, v30
	v_mul_f32_e32 v8, 0x3e16c740, v31
	v_cvt_pk_bf16_f32 v107, v3, v8
	v_mul_f32_e32 v3, 0x3e16c740, v24
	v_mul_f32_e32 v8, 0x3e16c740, v25
	v_cvt_pk_bf16_f32 v108, v3, v8
	v_mul_f32_e32 v3, 0x3e16c740, v27
	v_mul_f32_e32 v8, 0x3e16c740, v29
	v_cvt_pk_bf16_f32 v109, v3, v8
	v_mul_f32_e32 v3, 0x3e16c740, v34
	v_mul_f32_e32 v8, 0x3e16c740, v36
	v_cvt_pk_bf16_f32 v114, v3, v8
	v_mul_f32_e32 v3, 0x3e16c740, v38
	v_mul_f32_e32 v8, 0x3e16c740, v39
	v_cvt_pk_bf16_f32 v115, v3, v8
	v_mul_f32_e32 v3, 0x3e16c740, v32
	v_mul_f32_e32 v8, 0x3e16c740, v33
	v_cvt_pk_bf16_f32 v116, v3, v8
	v_mul_f32_e32 v3, 0x3e16c740, v35
	v_mul_f32_e32 v8, 0x3e16c740, v37
	v_cvt_pk_bf16_f32 v117, v3, v8
	v_mul_f32_e32 v3, 0x3e16c740, v49
	v_mul_f32_e32 v8, 0x3e16c740, v48
	v_cvt_pk_bf16_f32 v118, v3, v8
	v_mul_f32_e32 v3, 0x3e16c740, v46
	v_mul_f32_e32 v8, 0x3e16c740, v44
	v_cvt_pk_bf16_f32 v119, v3, v8
	v_mul_f32_e32 v3, 0x3e16c740, v47
	v_mul_f32_e32 v8, 0x3e16c740, v45
	v_cvt_pk_bf16_f32 v120, v3, v8
	v_mul_f32_e32 v3, 0x3e16c740, v43
	v_mul_f32_e32 v8, 0x3e16c740, v41
	v_cvt_pk_bf16_f32 v121, v3, v8
	v_mul_f32_e32 v3, 0x3e16c740, v12
	v_mul_f32_e32 v8, 0x3e16c740, v13
	v_cvt_pk_bf16_f32 v102, v3, v8
	v_mul_f32_e32 v3, 0x3e16c740, v14
	v_mul_f32_e32 v8, 0x3e16c740, v15
	v_cvt_pk_bf16_f32 v103, v3, v8
	v_mul_f32_e32 v3, 0x3e16c740, v40
	v_mul_f32_e32 v8, 0x3e16c740, v50
	v_cvt_pk_bf16_f32 v104, v3, v8
	v_mul_f32_e32 v3, 0x3e16c740, v52
	v_mul_f32_e32 v8, 0x3e16c740, v9
	v_cvt_pk_bf16_f32 v105, v3, v8
	v_mul_f32_e32 v3, 0x3e16c740, v10
	v_mul_f32_e32 v4, 0x3e16c740, v4
	v_cvt_pk_bf16_f32 v98, v3, v4
	v_mul_f32_e32 v3, 0x3e16c740, v5
	v_mul_f32_e32 v0, 0x3e16c740, v0
	v_readlane_b32 s4, v251, 44
	v_mul_f32_e32 v4, 0x3e16c740, v6
	v_cvt_pk_bf16_f32 v99, v3, v4
	v_mul_f32_e32 v3, 0x3e16c740, v7
	v_cvt_pk_bf16_f32 v100, v3, v0
	v_mul_f32_e32 v0, 0x3e16c740, v1
	v_mul_f32_e32 v1, 0x3e16c740, v2
	v_readlane_b32 s5, v251, 45
	v_cvt_pk_bf16_f32 v101, v0, v1
	s_mov_b64 s[12:13], s[40:41]
	s_mov_b64 s[14:15], s[34:35]
	v_mov_b32_e32 v0, 0
	v_mov_b32_e32 v1, 0
	v_mov_b32_e32 v2, 0
	v_mov_b32_e32 v3, 0
	v_mov_b32_e32 v4, 0
	v_mov_b32_e32 v5, 0
	v_mov_b32_e32 v6, 0
	v_mov_b32_e32 v7, 0
	v_mov_b32_e32 v8, 0
	v_mov_b32_e32 v9, 0
	v_mov_b32_e32 v10, 0
	v_mov_b32_e32 v11, 0
	v_mov_b32_e32 v12, 0
	v_mov_b32_e32 v13, 0
	v_mov_b32_e32 v14, 0
	v_mov_b32_e32 v15, 0
	v_mov_b32_e32 v16, 0
	v_mov_b32_e32 v17, 0
	v_mov_b32_e32 v18, 0
	v_mov_b32_e32 v19, 0
	v_mov_b32_e32 v20, 0
	v_mov_b32_e32 v21, 0
	v_mov_b32_e32 v22, 0
	v_mov_b32_e32 v23, 0
	v_mov_b32_e32 v24, 0
	v_mov_b32_e32 v25, 0
	v_mov_b32_e32 v26, 0
	v_mov_b32_e32 v27, 0
	v_mov_b32_e32 v28, 0
	v_mov_b32_e32 v29, 0
	v_mov_b32_e32 v30, 0
	v_mov_b32_e32 v31, 0
	v_mov_b32_e32 v147, 0
	s_waitcnt vmcnt(0)
	s_barrier
; DEV float max3f(float a, float b, float c) { return fmaxf(fmaxf(a, b), c); }
; DEV void attn_unit(int b, int h, int qb, const bf16_t* Q, const bf16_t* K, const bf16_t* V, bf16_t* O, LAS unsigned char* sh, const int tid, const float* qgain) {
;     ...
;     QKT(pA0, pA1, 0);
;     { float m0 = pA0[0];
; #pragma unroll
;         for (int r = 0; r < 16; ++r) m0 = max3f(m0, pA0[r], pA1[r]);
;         mrun = fmaxf(m0, __shfl_xor(m0, 32)); }
	ds_read_b128 v[196:199], v194 offset:0
	ds_read_b128 v[200:203], v194 offset:512
	ds_read_b128 v[204:207], v194 offset:2048
	ds_read_b128 v[208:211], v194 offset:2560
	ds_read_b128 v[212:215], v194 offset:4096
	ds_read_b128 v[216:219], v194 offset:4608
	s_waitcnt lgkmcnt(4)
	v_mfma_f32_32x32x16_bf16 v[48:63], v[196:199], v[110:113], 0
	ds_read_b128 v[196:199], v194 offset:6144
	v_mfma_f32_32x32x16_bf16 v[32:47], v[200:203], v[110:113], 0
	ds_read_b128 v[200:203], v194 offset:6656
	s_waitcnt lgkmcnt(4)
	v_mfma_f32_32x32x16_bf16 v[48:63], v[204:207], v[106:109], v[48:63]
	ds_read_b128 v[204:207], v194 offset:8192
	v_mfma_f32_32x32x16_bf16 v[32:47], v[208:211], v[106:109], v[32:47]
	ds_read_b128 v[208:211], v194 offset:8704
	s_waitcnt lgkmcnt(4)
	v_mfma_f32_32x32x16_bf16 v[48:63], v[212:215], v[114:117], v[48:63]
	ds_read_b128 v[212:215], v194 offset:10240
	v_mfma_f32_32x32x16_bf16 v[32:47], v[216:219], v[114:117], v[32:47]
	ds_read_b128 v[216:219], v194 offset:10752
	s_waitcnt lgkmcnt(4)
	v_mfma_f32_32x32x16_bf16 v[48:63], v[196:199], v[118:121], v[48:63]
	v_mfma_f32_32x32x16_bf16 v[32:47], v[200:203], v[118:121], v[32:47]
	s_waitcnt lgkmcnt(2)
	v_mfma_f32_32x32x16_bf16 v[48:63], v[204:207], v[102:105], v[48:63]
	v_mfma_f32_32x32x16_bf16 v[32:47], v[208:211], v[102:105], v[32:47]
	s_waitcnt lgkmcnt(0)
	v_mfma_f32_32x32x16_bf16 v[48:63], v[212:215], v[98:101], v[48:63]
	v_mfma_f32_32x32x16_bf16 v[32:47], v[216:219], v[98:101], v[32:47]
	s_nop 15
	s_nop 3
	v_max_f32_e32 v149, v48, v32
	v_max3_f32 v149, v149, v49, v33
	v_max3_f32 v149, v149, v50, v34
	v_max3_f32 v149, v149, v51, v35
	v_max3_f32 v149, v149, v52, v36
	v_max3_f32 v149, v149, v53, v37
	v_max3_f32 v149, v149, v54, v38
	v_max3_f32 v149, v149, v55, v39
	v_max3_f32 v149, v149, v56, v40
	v_max3_f32 v149, v149, v57, v41
	v_max3_f32 v149, v149, v58, v42
	v_max3_f32 v149, v149, v59, v43
	v_max3_f32 v149, v149, v60, v44
	v_max3_f32 v149, v149, v61, v45
	v_max3_f32 v149, v149, v62, v46
	v_max3_f32 v149, v149, v63, v47
	v_mov_b32_e32 v175, v149
	v_mov_b32_e32 v178, v149
	s_nop 1
	v_permlane32_swap_b32_e32 v175, v178
	v_max_f32_e32 v175, v175, v178
	ds_read_b128 v[196:199], v194 offset:20480
	ds_read_b128 v[200:203], v194 offset:20992
	ds_read_b128 v[204:207], v194 offset:22528
	ds_read_b128 v[208:211], v194 offset:23040
	ds_read_b64_tr_b16 v[220:221], v139 offset:0
	ds_read_b64_tr_b16 v[222:223], v139 offset:512
	ds_read_b64_tr_b16 v[244:245], v139 offset:4096
	ds_read_b64_tr_b16 v[246:247], v139 offset:4608
	ds_read_b128 v[212:215], v194 offset:24576
	ds_read_b128 v[216:219], v194 offset:25088
	v_xor_b32_e32 v224, 0x80000000, v175
	v_mov_b32_e32 v225, v224
	v_mov_b32_e32 v226, v224
	v_mov_b32_e32 v227, v224
	v_mov_b32_e32 v228, v224
	v_mov_b32_e32 v229, v224
	v_mov_b32_e32 v230, v224
	v_mov_b32_e32 v231, v224
	v_mov_b32_e32 v232, v224
	v_mov_b32_e32 v233, v224
	v_mov_b32_e32 v234, v224
	v_mov_b32_e32 v235, v224
	v_mov_b32_e32 v236, v224
	v_mov_b32_e32 v237, v224
	v_mov_b32_e32 v238, v224
	v_mov_b32_e32 v239, v224
	v_sub_f32_e32 v48, v48, v175
	v_sub_f32_e32 v49, v49, v175
	v_sub_f32_e32 v50, v50, v175
	v_sub_f32_e32 v51, v51, v175
	v_sub_f32_e32 v52, v52, v175
	v_sub_f32_e32 v53, v53, v175
	v_sub_f32_e32 v54, v54, v175
	v_sub_f32_e32 v55, v55, v175
	v_sub_f32_e32 v56, v56, v175
	v_sub_f32_e32 v57, v57, v175
	v_sub_f32_e32 v58, v58, v175
	v_sub_f32_e32 v59, v59, v175
	v_sub_f32_e32 v60, v60, v175
	v_sub_f32_e32 v61, v61, v175
	v_sub_f32_e32 v62, v62, v175
	v_sub_f32_e32 v63, v63, v175
	v_sub_f32_e32 v32, v32, v175
	v_sub_f32_e32 v33, v33, v175
	v_sub_f32_e32 v34, v34, v175
	v_sub_f32_e32 v35, v35, v175
	v_sub_f32_e32 v36, v36, v175
	v_sub_f32_e32 v37, v37, v175
	v_sub_f32_e32 v38, v38, v175
	v_sub_f32_e32 v39, v39, v175
	v_sub_f32_e32 v40, v40, v175
	v_sub_f32_e32 v41, v41, v175
	v_sub_f32_e32 v42, v42, v175
	v_sub_f32_e32 v43, v43, v175
	v_sub_f32_e32 v44, v44, v175
	v_sub_f32_e32 v45, v45, v175
	v_sub_f32_e32 v46, v46, v175
	v_sub_f32_e32 v47, v47, v175
	s_mov_b32 s24, 15
